# de-serialised epilogues: P6 residual epilogue batches its 36 loads with counted vmcnt; P10 final rms_norm store tail no longer waits per 16B (final_g slice preloaded once)
# speedup vs baseline: 1.0832x; 1.0451x over previous
;     __device__ __forceinline__ void operator()(const f32x4 (&acc)[2][2][4][2], const Unit& u, int wr, int wc, int fr, int fq) const {
;         const int row0 = u.pm * BM + wr * 64 + fr; const int col0 = u.pn * BM + wc * 32 + 4 * fq;
;         const float* gp = gate + (size_t)(u.pm >> 3) * gstride + col0;
; #pragma unroll
;         for (int bj = 0; bj < 2; ++bj)
; #pragma unroll
;             for (int n = 0; n < 2; ++n) { const f32x4 g4 = *(const f32x4*)(gp + bj * HALF + n * 16);
; #pragma unroll
;                 for (int ai = 0; ai < 2; ++ai)
; #pragma unroll
;                     for (int m = 0; m < 4; ++m) { const size_t off = (size_t)(row0 + ai * HALF + m * 16) * 2048 + col0 + bj * HALF + n * 16;
;                         const f32x4 xv = *(const f32x4*)(x + off); *(f32x4*)(out + off) = xv + g4 * acc[ai][bj][m][n]; }
;                 asm volatile("" ::: "memory"); }
.LBB0_584:
	v_lshl_add_u32 v170, s38, 8, v129
	v_lshl_or_b32 v172, s57, 8, v133
	s_ashr_i32 s18, s38, 3
	s_mul_hi_i32 s19, s18, 0xc000
	s_mul_i32 s18, s18, 0xc000
	s_add_u32 s18, s50, s18
	s_addc_u32 s19, s51, s19
	v_lshlrev_b32_e32 v171, 2, v172
	v_lshl_add_u32 v173, v170, 11, v172
	v_lshlrev_b32_e32 v173, 2, v173
	v_add_u32_e32 v174, 0x20000, v173
	v_add_u32_e32 v175, 0x40000, v173
	v_add_u32_e32 v176, 0x60000, v173
	v_add_u32_e32 v177, 0x100000, v173
	v_add_u32_e32 v178, 0x120000, v173
	v_add_u32_e32 v179, 0x140000, v173
	v_add_u32_e32 v180, 0x160000, v173
	s_andn2_b64 vcc, exec, s[0:1]
	s_mov_b64 s[0:1], -1
	global_load_dwordx4 v[152:155], v171, s[18:19]
	global_load_dwordx4 v[156:159], v171, s[18:19] offset:64
	global_load_dwordx4 v[160:163], v171, s[18:19] offset:512
	global_load_dwordx4 v[164:167], v171, s[18:19] offset:576
	global_load_dwordx4 v[184:187], v173, s[36:37]
	global_load_dwordx4 v[188:191], v174, s[36:37]
	global_load_dwordx4 v[192:195], v175, s[36:37]
	global_load_dwordx4 v[196:199], v176, s[36:37]
	global_load_dwordx4 v[200:203], v177, s[36:37]
	global_load_dwordx4 v[204:207], v178, s[36:37]
	global_load_dwordx4 v[208:211], v179, s[36:37]
	global_load_dwordx4 v[212:215], v180, s[36:37]
	global_load_dwordx4 v[216:219], v173, s[36:37] offset:64
	global_load_dwordx4 v[220:223], v174, s[36:37] offset:64
	global_load_dwordx4 v[224:227], v175, s[36:37] offset:64
	global_load_dwordx4 v[228:231], v176, s[36:37] offset:64
	global_load_dwordx4 v[232:235], v177, s[36:37] offset:64
	global_load_dwordx4 v[236:239], v178, s[36:37] offset:64
	global_load_dwordx4 v[240:243], v179, s[36:37] offset:64
	global_load_dwordx4 v[244:247], v180, s[36:37] offset:64
	s_waitcnt vmcnt(15)
	v_pk_fma_f32 v[124:125], v[124:125], v[152:153], v[184:185]
	v_pk_fma_f32 v[126:127], v[126:127], v[154:155], v[186:187]
	global_store_dwordx4 v173, v[124:127], s[90:91]
	s_waitcnt vmcnt(15)
	v_pk_fma_f32 v[120:121], v[120:121], v[152:153], v[188:189]
	v_pk_fma_f32 v[122:123], v[122:123], v[154:155], v[190:191]
	global_store_dwordx4 v174, v[120:123], s[90:91]
	s_waitcnt vmcnt(15)
	v_pk_fma_f32 v[116:117], v[116:117], v[152:153], v[192:193]
	v_pk_fma_f32 v[118:119], v[118:119], v[154:155], v[194:195]
	global_store_dwordx4 v175, v[116:119], s[90:91]
	s_waitcnt vmcnt(15)
	v_pk_fma_f32 v[112:113], v[112:113], v[152:153], v[196:197]
	v_pk_fma_f32 v[114:115], v[114:115], v[154:155], v[198:199]
	global_store_dwordx4 v176, v[112:115], s[90:91]
	s_waitcnt vmcnt(15)
	v_pk_fma_f32 v[108:109], v[108:109], v[152:153], v[200:201]
	v_pk_fma_f32 v[110:111], v[110:111], v[154:155], v[202:203]
	global_store_dwordx4 v177, v[108:111], s[90:91]
	s_waitcnt vmcnt(15)
	v_pk_fma_f32 v[96:97], v[96:97], v[152:153], v[204:205]
	v_pk_fma_f32 v[98:99], v[98:99], v[154:155], v[206:207]
	global_store_dwordx4 v178, v[96:99], s[90:91]
	s_waitcnt vmcnt(15)
	v_pk_fma_f32 v[88:89], v[88:89], v[152:153], v[208:209]
	v_pk_fma_f32 v[90:91], v[90:91], v[154:155], v[210:211]
	global_store_dwordx4 v179, v[88:91], s[90:91]
	s_waitcnt vmcnt(15)
	v_pk_fma_f32 v[80:81], v[80:81], v[152:153], v[212:213]
	v_pk_fma_f32 v[82:83], v[82:83], v[154:155], v[214:215]
	global_store_dwordx4 v180, v[80:83], s[90:91]
	global_load_dwordx4 v[184:187], v173, s[36:37] offset:512
	global_load_dwordx4 v[188:191], v174, s[36:37] offset:512
	global_load_dwordx4 v[192:195], v175, s[36:37] offset:512
	global_load_dwordx4 v[196:199], v176, s[36:37] offset:512
	global_load_dwordx4 v[200:203], v177, s[36:37] offset:512
	global_load_dwordx4 v[204:207], v178, s[36:37] offset:512
	global_load_dwordx4 v[208:211], v179, s[36:37] offset:512
	global_load_dwordx4 v[212:215], v180, s[36:37] offset:512
	s_waitcnt vmcnt(23)
	v_pk_fma_f32 v[104:105], v[104:105], v[156:157], v[216:217]
	v_pk_fma_f32 v[106:107], v[106:107], v[158:159], v[218:219]
	global_store_dwordx4 v173, v[104:107], s[90:91] offset:64
	s_waitcnt vmcnt(23)
	v_pk_fma_f32 v[100:101], v[100:101], v[156:157], v[220:221]
	v_pk_fma_f32 v[102:103], v[102:103], v[158:159], v[222:223]
	global_store_dwordx4 v174, v[100:103], s[90:91] offset:64
	s_waitcnt vmcnt(23)
	v_pk_fma_f32 v[92:93], v[92:93], v[156:157], v[224:225]
	v_pk_fma_f32 v[94:95], v[94:95], v[158:159], v[226:227]
	global_store_dwordx4 v175, v[92:95], s[90:91] offset:64
	s_waitcnt vmcnt(23)
	v_pk_fma_f32 v[84:85], v[84:85], v[156:157], v[228:229]
	v_pk_fma_f32 v[86:87], v[86:87], v[158:159], v[230:231]
	global_store_dwordx4 v176, v[84:87], s[90:91] offset:64
	s_waitcnt vmcnt(23)
;     __device__ __forceinline__ void operator()(const f32x4 (&acc)[2][2][4][2], const Unit& u, int wr, int wc, int fr, int fq) const {
;     ...
;             for (int n = 0; n < 2; ++n) { const f32x4 g4 = *(const f32x4*)(gp + bj * HALF + n * 16);
; #pragma unroll
;                 for (int ai = 0; ai < 2; ++ai)
; #pragma unroll
;                     for (int m = 0; m < 4; ++m) { const size_t off = (size_t)(row0 + ai * HALF + m * 16) * 2048 + col0 + bj * HALF + n * 16;
;                         const f32x4 xv = *(const f32x4*)(x + off); *(f32x4*)(out + off) = xv + g4 * acc[ai][bj][m][n]; }
;                 asm volatile("" ::: "memory"); }
	v_pk_fma_f32 v[76:77], v[76:77], v[156:157], v[232:233]
	v_pk_fma_f32 v[78:79], v[78:79], v[158:159], v[234:235]
	global_store_dwordx4 v177, v[76:79], s[90:91] offset:64
	s_waitcnt vmcnt(23)
	v_pk_fma_f32 v[68:69], v[68:69], v[156:157], v[236:237]
	v_pk_fma_f32 v[70:71], v[70:71], v[158:159], v[238:239]
	global_store_dwordx4 v178, v[68:71], s[90:91] offset:64
	s_waitcnt vmcnt(23)
	v_pk_fma_f32 v[60:61], v[60:61], v[156:157], v[240:241]
	v_pk_fma_f32 v[62:63], v[62:63], v[158:159], v[242:243]
	global_store_dwordx4 v179, v[60:63], s[90:91] offset:64
	s_waitcnt vmcnt(23)
	v_pk_fma_f32 v[52:53], v[52:53], v[156:157], v[244:245]
	v_pk_fma_f32 v[54:55], v[54:55], v[158:159], v[246:247]
	global_store_dwordx4 v180, v[52:55], s[90:91] offset:64
	global_load_dwordx4 v[216:219], v173, s[36:37] offset:576
	global_load_dwordx4 v[220:223], v174, s[36:37] offset:576
	global_load_dwordx4 v[224:227], v175, s[36:37] offset:576
	global_load_dwordx4 v[228:231], v176, s[36:37] offset:576
	global_load_dwordx4 v[232:235], v177, s[36:37] offset:576
	global_load_dwordx4 v[236:239], v178, s[36:37] offset:576
	global_load_dwordx4 v[240:243], v179, s[36:37] offset:576
	global_load_dwordx4 v[244:247], v180, s[36:37] offset:576
	s_waitcnt vmcnt(23)
	v_pk_fma_f32 v[72:73], v[72:73], v[160:161], v[184:185]
	v_pk_fma_f32 v[74:75], v[74:75], v[162:163], v[186:187]
	global_store_dwordx4 v173, v[72:75], s[90:91] offset:512
	s_waitcnt vmcnt(23)
	v_pk_fma_f32 v[64:65], v[64:65], v[160:161], v[188:189]
	v_pk_fma_f32 v[66:67], v[66:67], v[162:163], v[190:191]
	global_store_dwordx4 v174, v[64:67], s[90:91] offset:512
	s_waitcnt vmcnt(23)
	v_pk_fma_f32 v[56:57], v[56:57], v[160:161], v[192:193]
	v_pk_fma_f32 v[58:59], v[58:59], v[162:163], v[194:195]
	global_store_dwordx4 v175, v[56:59], s[90:91] offset:512
	s_waitcnt vmcnt(23)
	v_pk_fma_f32 v[48:49], v[48:49], v[160:161], v[196:197]
	v_pk_fma_f32 v[50:51], v[50:51], v[162:163], v[198:199]
	global_store_dwordx4 v176, v[48:51], s[90:91] offset:512
	s_waitcnt vmcnt(23)
	v_pk_fma_f32 v[40:41], v[40:41], v[160:161], v[200:201]
	v_pk_fma_f32 v[42:43], v[42:43], v[162:163], v[202:203]
	global_store_dwordx4 v177, v[40:43], s[90:91] offset:512
	s_waitcnt vmcnt(23)
	v_pk_fma_f32 v[32:33], v[32:33], v[160:161], v[204:205]
	v_pk_fma_f32 v[34:35], v[34:35], v[162:163], v[206:207]
	global_store_dwordx4 v178, v[32:35], s[90:91] offset:512
	s_waitcnt vmcnt(23)
	v_pk_fma_f32 v[24:25], v[24:25], v[160:161], v[208:209]
	v_pk_fma_f32 v[26:27], v[26:27], v[162:163], v[210:211]
	global_store_dwordx4 v179, v[24:27], s[90:91] offset:512
	s_waitcnt vmcnt(23)
	v_pk_fma_f32 v[16:17], v[16:17], v[160:161], v[212:213]
	v_pk_fma_f32 v[18:19], v[18:19], v[162:163], v[214:215]
	global_store_dwordx4 v180, v[16:19], s[90:91] offset:512
	s_waitcnt vmcnt(15)
	v_pk_fma_f32 v[44:45], v[44:45], v[164:165], v[216:217]
	v_pk_fma_f32 v[46:47], v[46:47], v[166:167], v[218:219]
	global_store_dwordx4 v173, v[44:47], s[90:91] offset:576
	s_waitcnt vmcnt(15)
	v_pk_fma_f32 v[36:37], v[36:37], v[164:165], v[220:221]
	v_pk_fma_f32 v[38:39], v[38:39], v[166:167], v[222:223]
	global_store_dwordx4 v174, v[36:39], s[90:91] offset:576
	s_waitcnt vmcnt(15)
	v_pk_fma_f32 v[28:29], v[28:29], v[164:165], v[224:225]
	v_pk_fma_f32 v[30:31], v[30:31], v[166:167], v[226:227]
	global_store_dwordx4 v175, v[28:31], s[90:91] offset:576
	s_waitcnt vmcnt(15)
	v_pk_fma_f32 v[20:21], v[20:21], v[164:165], v[228:229]
	v_pk_fma_f32 v[22:23], v[22:23], v[166:167], v[230:231]
	global_store_dwordx4 v176, v[20:23], s[90:91] offset:576
	s_waitcnt vmcnt(15)
	v_pk_fma_f32 v[12:13], v[12:13], v[164:165], v[232:233]
	v_pk_fma_f32 v[14:15], v[14:15], v[166:167], v[234:235]
	global_store_dwordx4 v177, v[12:15], s[90:91] offset:576
	s_waitcnt vmcnt(15)
	v_pk_fma_f32 v[8:9], v[8:9], v[164:165], v[236:237]
	v_pk_fma_f32 v[10:11], v[10:11], v[166:167], v[238:239]
	global_store_dwordx4 v178, v[8:11], s[90:91] offset:576
	s_waitcnt vmcnt(15)
	v_pk_fma_f32 v[4:5], v[4:5], v[164:165], v[240:241]
	v_pk_fma_f32 v[6:7], v[6:7], v[166:167], v[242:243]
	global_store_dwordx4 v179, v[4:7], s[90:91] offset:576
	s_waitcnt vmcnt(15)
	v_pk_fma_f32 v[0:1], v[0:1], v[164:165], v[244:245]
	v_pk_fma_f32 v[2:3], v[2:3], v[166:167], v[246:247]
	global_store_dwordx4 v180, v[0:3], s[90:91] offset:576
	s_cbranch_vccnz .LBB0_573
	s_andn2_b64 vcc, exec, s[6:7]
	s_cbranch_vccnz .LBB0_572
	s_barrier
	s_branch .LBB0_572

; __device__ __forceinline__ float bf_lo(unsigned u) { return __uint_as_float(u << 16); }
; __device__ __forceinline__ float bf_hi(unsigned u) { return __uint_as_float(u & 0xffff0000u); }
; __global__ void __launch_bounds__(NT, 2) mk_fwd(Args args) {
;     ...
;     if (IN(10)) {
;         const float* fg = args.in[28];
;         for (int tok = gw; tok < MTOK; tok += NGW) {
;             const int b = tok >> 11;
;             f32x2 hf2[16];
; #pragma unroll
;             for (int j = 0; j < 4; ++j) { const u32x4 a = *(const u32x4*)(HB + (size_t)tok * DM + lane * 32 + j * 8);
; #pragma unroll
;                 for (int q = 0; q < 4; ++q) hf2[j * 4 + q] = (f32x2){bf_lo(a[q]), bf_hi(a[q])}; }
;             const int e0 = EIDX[(size_t)tok * 128 + lane], e1 = EIDX[(size_t)tok * 128 + 64 + lane];
;             const float g0 = GATE[(size_t)tok * 128 + lane], g1 = GATE[(size_t)tok * 128 + 64 + lane];
;             const bool hi32 = (lane & 32) != 0, hi16 = (lane & 16) != 0; const int l3 = (lane & 3) << 4;
;     ...
;             float* xr = args.out + (size_t)tok * DM + lane * 32; const float* gt2 = MOD + (size_t)b * NMODC + 5 * DM + lane * 32;
;             float ss = 0.f;
; #pragma unroll
;             for (int q = 0; q < 8; ++q) { const f32x4 xv = *(const f32x4*)(xr + q * 4), g4 = *(const f32x4*)(gt2 + q * 4);
.LBB0_883:
	s_cmp_lt_i32 s94, 11
	s_cselect_b64 s[2:3], -1, 0
	s_and_b64 s[0:1], s[2:3], s[0:1]
	s_and_b64 s[0:1], s[0:1], s[86:87]
	s_andn2_b64 vcc, exec, s[0:1]
	s_cbranch_vccnz .LBB0_913
	s_waitcnt vmcnt(0)
	v_mbcnt_hi_u32_b32 v3, -1, v169
	v_and_b32_e32 v5, 64, v3
	v_xor_b32_e32 v4, 32, v3
	v_add_u32_e32 v6, 64, v5
	v_cmp_lt_i32_e32 vcc, v4, v6
	v_mov_b32_e32 v137, 0
	v_and_b32_e32 v0, 32, v168
	v_cndmask_b32_e32 v4, v3, v4, vcc
	v_cmp_eq_u32_e64 s[0:1], 0, v0
	v_and_b32_e32 v0, 16, v168
	v_mov_b32_e32 v131, v137
	v_lshlrev_b32_e32 v129, 2, v4
	v_xor_b32_e32 v4, 16, v3
	v_cmp_eq_u32_e64 s[2:3], 0, v0
	v_lshlrev_b32_e32 v2, 4, v168
	v_lshl_add_u64 v[0:1], s[92:93], 0, v[130:131]
	s_mov_b64 s[4:5], 0x2a00000
	v_cmp_lt_i32_e32 vcc, v4, v6
	s_add_u32 s6, s92, 0x6a00000
	v_lshl_add_u64 v[96:97], s[80:81], 0, v[136:137]
	v_lshl_add_u64 v[98:99], v[0:1], 0, s[4:5]
	v_cndmask_b32_e32 v3, v3, v4, vcc
	v_and_or_b32 v2, v2, 48, v5
	s_mov_b64 s[4:5], 0x4a00000
	v_lshlrev_b32_e32 v136, 7, v128
	v_and_b32_e32 v148, 60, v128
	s_addc_u32 s7, s93, 0
	v_lshlrev_b32_e32 v146, 2, v3
	v_lshlrev_b32_e32 v147, 2, v2
	v_lshl_add_u64 v[100:101], v[0:1], 0, s[4:5]
	v_lshl_add_u64 v[102:103], s[90:91], 0, v[136:137]
	v_lshl_add_u64 v[104:105], s[88:89], 0, v[136:137]
	v_add_u32_e32 v149, -12, v148
	v_add_u32_e32 v150, -8, v148
	v_add_u32_e32 v151, -4, v148
	s_mov_b32 s11, 0x378e98ab
	s_mov_b32 s13, 0x3b7cd369
	s_mov_b32 s15, 0xbcc618b2
	s_mov_b32 s17, 0x3dda74e4
	s_mov_b32 s19, 0x3f228afd
	s_mov_b32 s21, 0x3e03c728
	s_mov_b32 s23, 0xbfb8aa3b
	s_mov_b32 s25, 0x42ce8ed0
	s_mov_b32 s26, 0xc2b17218
	v_mov_b32_e32 v152, 0x3ba10414
	s_brev_b32 s27, -2
	v_lshlrev_b32_e32 v136, 2, v138
	s_mov_b64 s[8:9], 0xa000
	s_mov_b32 s28, 0xa000
	v_mov_b32_e32 v153, 0x358637bd
	s_mov_b32 s29, 0x800000
	v_mov_b32_e32 v154, 0xb9c68948
	v_mov_b32_e32 v155, 0x7f800000
	s_mov_b32 s50, 0x55555555
	s_mov_b32 s51, 0x55555555
	s_mov_b32 s52, 0x33333333
	s_mov_b32 s53, 0x33333333
	s_mov_b32 s54, 0xf0f0f0f
	s_mov_b32 s55, 0xf0f0f0f
	s_mov_b32 s56, 0xff00ff
	s_mov_b32 s57, 0xff00ff
	s_mov_b32 s58, 0xffff
	s_mov_b32 s59, 0xffff
	s_mov_b32 s60, -1
	s_mov_b32 s61, 0
	global_load_dwordx4 v[186:189], v[104:105], off
	global_load_dwordx4 v[190:193], v[104:105], off offset:16
	global_load_dwordx4 v[194:197], v[104:105], off offset:32
	global_load_dwordx4 v[198:201], v[104:105], off offset:48
	global_load_dwordx4 v[202:205], v[104:105], off offset:64
	global_load_dwordx4 v[206:209], v[104:105], off offset:80
	global_load_dwordx4 v[210:213], v[104:105], off offset:96
	global_load_dwordx4 v[214:217], v[104:105], off offset:112
	s_waitcnt vmcnt(0)
	s_branch .LBB0_886
.LBB0_885:
	s_ashr_i32 s10, s70, 11
	s_lshl_b64 s[4:5], s[70:71], 13
	v_lshl_add_u64 v[0:1], v[102:103], 0, s[4:5]
	s_mul_hi_i32 s5, s10, 0xc000
	s_mul_i32 s10, s10, 0xc000
	s_add_u32 s4, s74, s10
	s_addc_u32 s5, s75, s5
	v_lshl_add_u64 v[54:55], s[4:5], 0, v[136:137]
	v_lshl_add_u64 v[66:67], v[54:55], 0, s[8:9]
	global_load_dwordx4 v[2:5], v[0:1], off offset:48
	global_load_dwordx4 v[6:9], v[0:1], off offset:32
	global_load_dwordx4 v[10:13], v[0:1], off offset:16
	global_load_dwordx4 v[14:17], v[0:1], off
	global_load_dwordx4 v[18:21], v[66:67], off offset:32
	global_load_dwordx4 v[22:25], v[66:67], off offset:16
	global_load_dwordx4 v[26:29], v[66:67], off offset:48
	global_load_dwordx4 v[30:33], v[0:1], off offset:96
	global_load_dwordx4 v[34:37], v[0:1], off offset:80
	global_load_dwordx4 v[38:41], v[0:1], off offset:64
	global_load_dwordx4 v[42:45], v[66:67], off offset:64
	global_load_dwordx4 v[46:49], v[66:67], off offset:96
	global_load_dwordx4 v[50:53], v[66:67], off offset:80
	v_add_co_u32_e32 v68, vcc, s28, v54
	s_add_i32 s70, s70, s72
	s_nop 0
	v_addc_co_u32_e32 v69, vcc, 0, v55, vcc
	global_load_dwordx4 v[54:57], v[68:69], off
	global_load_dwordx4 v[58:61], v[0:1], off offset:112
	global_load_dwordx4 v[62:65], v[66:67], off offset:112
	s_cmpk_gt_i32 s70, 0x3fff
	s_waitcnt vmcnt(11)
	v_pk_fma_f32 v[6:7], v[18:19], v[140:141], v[6:7]
	s_waitcnt vmcnt(10)
	v_pk_fma_f32 v[10:11], v[22:23], v[144:145], v[10:11]
	v_pk_fma_f32 v[12:13], v[24:25], v[142:143], v[12:13]
	v_pk_fma_f32 v[8:9], v[20:21], v[138:139], v[8:9]
	s_waitcnt vmcnt(9)
	v_pk_fma_f32 v[18:19], v[26:27], v[134:135], v[2:3]
	v_pk_fma_f32 v[20:21], v[28:29], v[132:133], v[4:5]
	s_waitcnt vmcnt(2)
; __device__ __forceinline__ float wave_sum(float v) { v = row16_sum(v); v += __shfl_xor(v, 16); v += __shfl_xor(v, 32); return v; }
; __global__ void __launch_bounds__(NT, 2) mk_fwd(Args args) {
;     ...
;             for (int q = 0; q < 8; ++q) { const f32x4 xv = *(const f32x4*)(xr + q * 4), g4 = *(const f32x4*)(gt2 + q * 4);
;                 float* a = acc + q * 4;
;                 a[0] = xv.x + g4.x * a[0]; a[1] = xv.y + g4.y * a[1]; a[2] = xv.z + g4.z * a[2]; a[3] = xv.w + g4.w * a[3];
;                 ss += (a[0] * a[0] + a[1] * a[1]) + (a[2] * a[2] + a[3] * a[3]); }
;             ss = wave_sum(ss);
;             const float rinv = rsqrtf(ss * (1.0f / DM) + 1e-6f);
; #pragma unroll
;             for (int q = 0; q < 8; ++q) { const f32x4 f4 = *(const f32x4*)(fg + lane * 32 + q * 4); const float* a = acc + q * 4;
;                 *(f32x4*)(xr + q * 4) = (f32x4){a[0] * rinv * f4.x, a[1] * rinv * f4.y, a[2] * rinv * f4.z, a[3] * rinv * f4.w}; }
	v_pk_fma_f32 v[2:3], v[54:55], v[118:119], v[14:15]
	v_pk_fma_f32 v[4:5], v[56:57], v[122:123], v[16:17]
	v_pk_fma_f32 v[28:29], v[52:53], v[120:121], v[36:37]
	v_mov_b32_e32 v17, v11
	v_mov_b32_e32 v37, v13
	v_mov_b32_e32 v16, v3
	v_mov_b32_e32 v36, v5
	v_pk_fma_f32 v[24:25], v[44:45], v[126:127], v[40:41]
	v_pk_fma_f32 v[26:27], v[50:51], v[124:125], v[34:35]
	v_mov_b32_e32 v15, v10
	v_mov_b32_e32 v35, v12
	v_mov_b32_e32 v40, v7
	v_mov_b32_e32 v41, v9
	v_mov_b32_e32 v14, v2
	v_mov_b32_e32 v34, v4
	v_pk_mul_f32 v[16:17], v[16:17], v[16:17]
	v_pk_mul_f32 v[36:37], v[36:37], v[36:37]
	v_pk_fma_f32 v[22:23], v[42:43], v[130:131], v[38:39]
	v_mov_b32_e32 v38, v6
	v_mov_b32_e32 v39, v8
	v_pk_mul_f32 v[40:41], v[40:41], v[40:41]
	v_pk_fma_f32 v[14:15], v[14:15], v[14:15], v[16:17]
	v_pk_fma_f32 v[16:17], v[34:35], v[34:35], v[36:37]
	v_mul_f32_e32 v42, v19, v19
	v_mul_f32_e32 v44, v21, v21
	v_pk_fma_f32 v[38:39], v[38:39], v[38:39], v[40:41]
	v_pk_add_f32 v[14:15], v[14:15], v[16:17]
	v_pk_fma_f32 v[30:31], v[46:47], v[116:117], v[30:31]
	v_pk_fma_f32 v[32:33], v[48:49], v[114:115], v[32:33]
	v_pk_mul_f32 v[46:47], v[22:23], v[22:23]
	v_pk_mul_f32 v[48:49], v[24:25], v[24:25]
	v_pk_fma_f32 v[42:43], v[18:19], v[18:19], v[42:43] op_sel_hi:[1,1,0]
	v_pk_fma_f32 v[44:45], v[20:21], v[20:21], v[44:45] op_sel_hi:[1,1,0]
	v_pk_add_f32 v[34:35], v[38:39], v[38:39] op_sel:[0,1] op_sel_hi:[1,0]
	v_pk_add_f32 v[14:15], v[14:15], v[14:15] op_sel:[0,1] op_sel_hi:[1,0]
	v_mov_b32_e32 v52, v27
	v_mov_b32_e32 v53, v29
	v_mov_b32_e32 v43, v48
	v_mov_b32_e32 v45, v49
	v_mov_b32_e32 v35, v47
	v_mov_b32_e32 v15, v46
	v_mov_b32_e32 v50, v26
	v_mov_b32_e32 v51, v28
	v_pk_mul_f32 v[52:53], v[52:53], v[52:53]
	v_pk_add_f32 v[36:37], v[42:43], v[44:45]
	v_pk_add_f32 v[14:15], v[14:15], v[34:35]
	v_mul_f32_e32 v54, v31, v31
	v_mul_f32_e32 v56, v33, v33
	s_waitcnt vmcnt(0)
	v_pk_fma_f32 v[58:59], v[62:63], v[112:113], v[58:59]
	v_pk_fma_f32 v[60:61], v[64:65], v[110:111], v[60:61]
	v_pk_fma_f32 v[40:41], v[50:51], v[50:51], v[52:53]
	v_pk_add_f32 v[14:15], v[14:15], v[36:37]
	v_pk_fma_f32 v[54:55], v[30:31], v[30:31], v[54:55] op_sel_hi:[1,1,0]
	v_pk_fma_f32 v[56:57], v[32:33], v[32:33], v[56:57] op_sel_hi:[1,1,0]
	v_pk_mul_f32 v[62:63], v[58:59], v[58:59]
	v_pk_mul_f32 v[64:65], v[60:61], v[60:61]
	v_pk_add_f32 v[38:39], v[40:41], v[40:41] op_sel:[0,1] op_sel_hi:[1,0]
	v_pk_add_f32 v[14:15], v[14:15], v[14:15] op_sel:[0,1] op_sel_hi:[1,0]
	v_mov_b32_e32 v55, v64
	v_mov_b32_e32 v39, v63
	v_mov_b32_e32 v15, v62
	v_mov_b32_e32 v57, v65
	v_pk_add_f32 v[14:15], v[14:15], v[38:39]
	v_pk_add_f32 v[16:17], v[54:55], v[56:57]
	s_nop 0
	v_pk_add_f32 v[14:15], v[14:15], v[16:17]
	s_nop 0
	v_add_f32_e32 v14, v14, v15
	s_nop 1
	v_add_f32_dpp v14, v14, v14 quad_perm:[1,0,3,2] row_mask:0xf bank_mask:0xf bound_ctrl:1
	s_nop 1
	v_add_f32_dpp v14, v14, v14 quad_perm:[2,3,0,1] row_mask:0xf bank_mask:0xf bound_ctrl:1
	s_nop 1
	v_add_f32_dpp v14, v14, v14 row_half_mirror row_mask:0xf bank_mask:0xf bound_ctrl:1
	s_nop 1
	v_add_f32_dpp v14, v14, v14 row_mirror row_mask:0xf bank_mask:0xf bound_ctrl:1
	ds_bpermute_b32 v15, v146, v14
	s_waitcnt lgkmcnt(0)
	v_add_f32_e32 v14, v14, v15
	ds_bpermute_b32 v15, v129, v14
	s_waitcnt lgkmcnt(0)
	v_add_f32_e32 v14, v14, v15
	v_fmamk_f32 v14, v14, 0x3a000000, v153
	v_mul_f32_e32 v15, 0x4b800000, v14
	v_cmp_gt_f32_e32 vcc, s29, v14
	s_nop 1
	v_cndmask_b32_e32 v14, v14, v15, vcc
	v_rsq_f32_e32 v14, v14
	s_nop 0
	v_mul_f32_e32 v15, 0x45800000, v14
	v_cndmask_b32_e32 v14, v14, v15, vcc
	v_pk_mul_f32 v[2:3], v[14:15], v[2:3] op_sel_hi:[0,1]
	v_pk_mul_f32 v[4:5], v[14:15], v[4:5] op_sel_hi:[0,1]
	v_pk_mul_f32 v[10:11], v[14:15], v[10:11] op_sel_hi:[0,1]
	v_pk_mul_f32 v[12:13], v[14:15], v[12:13] op_sel_hi:[0,1]
	v_pk_mul_f32 v[6:7], v[14:15], v[6:7] op_sel_hi:[0,1]
	v_pk_mul_f32 v[8:9], v[14:15], v[8:9] op_sel_hi:[0,1]
	v_pk_mul_f32 v[18:19], v[14:15], v[18:19] op_sel_hi:[0,1]
	v_pk_mul_f32 v[20:21], v[14:15], v[20:21] op_sel_hi:[0,1]
	v_pk_mul_f32 v[22:23], v[14:15], v[22:23] op_sel_hi:[0,1]
	v_pk_mul_f32 v[24:25], v[14:15], v[24:25] op_sel_hi:[0,1]
	v_pk_mul_f32 v[26:27], v[14:15], v[26:27] op_sel_hi:[0,1]
	v_pk_mul_f32 v[28:29], v[14:15], v[28:29] op_sel_hi:[0,1]
	v_pk_mul_f32 v[30:31], v[14:15], v[30:31] op_sel_hi:[0,1]
	v_pk_mul_f32 v[32:33], v[14:15], v[32:33] op_sel_hi:[0,1]
	v_pk_mul_f32 v[58:59], v[14:15], v[58:59] op_sel_hi:[0,1]
	v_pk_mul_f32 v[60:61], v[14:15], v[60:61] op_sel_hi:[0,1]
	v_pk_mul_f32 v[2:3], v[186:187], v[2:3]
	v_pk_mul_f32 v[4:5], v[188:189], v[4:5]
	global_store_dwordx4 v[0:1], v[2:5], off
	v_pk_mul_f32 v[10:11], v[190:191], v[10:11]
	v_pk_mul_f32 v[12:13], v[192:193], v[12:13]
	global_store_dwordx4 v[0:1], v[10:13], off offset:16
	v_pk_mul_f32 v[6:7], v[194:195], v[6:7]
	v_pk_mul_f32 v[8:9], v[196:197], v[8:9]
	global_store_dwordx4 v[0:1], v[6:9], off offset:32
	v_pk_mul_f32 v[18:19], v[198:199], v[18:19]
	v_pk_mul_f32 v[20:21], v[200:201], v[20:21]
	global_store_dwordx4 v[0:1], v[18:21], off offset:48
	v_pk_mul_f32 v[22:23], v[202:203], v[22:23]
	v_pk_mul_f32 v[24:25], v[204:205], v[24:25]
	global_store_dwordx4 v[0:1], v[22:25], off offset:64
	v_pk_mul_f32 v[26:27], v[206:207], v[26:27]
	v_pk_mul_f32 v[28:29], v[208:209], v[28:29]
	global_store_dwordx4 v[0:1], v[26:29], off offset:80
	v_pk_mul_f32 v[30:31], v[210:211], v[30:31]
	v_pk_mul_f32 v[32:33], v[212:213], v[32:33]
	global_store_dwordx4 v[0:1], v[30:33], off offset:96
	v_pk_mul_f32 v[58:59], v[214:215], v[58:59]
	v_pk_mul_f32 v[60:61], v[216:217], v[60:61]
	global_store_dwordx4 v[0:1], v[58:61], off offset:112
	s_cbranch_scc1 .LBB0_913
